# adds: GLA chunk cumsum LDS reads batched 2x32 (was 32 dependent round trips), pipelined K-loop for FFN-up s=0 GEMM without extra prefetch loads, SWIGLU epilogue chains interleaved 16-wide
# speedup vs baseline: 1.0544x; 1.0298x over previous
; DI float silu_f(float x) { return x * __builtin_amdgcn_rcpf(1.f + __expf(-x)); }
; template <int EPI, int MI>
; DI void gemm_tile(const GemmDesc& g, int tm, int tn, char* smem) {
;     ...
;   if (EPI == EPI_SWIGLU) {
;     u16* es = (u16*)smem;
; #pragma unroll
;     for (int mi = 0; mi < MI; ++mi)
; #pragma unroll
;       for (int i = 0; i < 16; ++i) {
;         const int lrow = wm * (32 * MI) + mi * 32 + (i & 3) + 8 * (i >> 2) + 4 * hh;
;         es[lrow * 64 + wn * 32 + r] = f2bf(silu_f(acc[mi][0][i]) * acc[mi][1][i]);
;       }
.LBB0_201:
	s_nop 1
	v_mul_f32_e32 v162, 0xbfb8aa3b, v80
	v_mul_f32_e32 v163, 0xbfb8aa3b, v81
	v_mul_f32_e32 v164, 0xbfb8aa3b, v82
	v_mul_f32_e32 v165, 0xbfb8aa3b, v83
	v_mul_f32_e32 v166, 0xbfb8aa3b, v84
	v_mul_f32_e32 v167, 0xbfb8aa3b, v85
	v_mul_f32_e32 v168, 0xbfb8aa3b, v86
	v_mul_f32_e32 v169, 0xbfb8aa3b, v87
	v_mul_f32_e32 v170, 0xbfb8aa3b, v88
	v_mul_f32_e32 v171, 0xbfb8aa3b, v89
	v_mul_f32_e32 v172, 0xbfb8aa3b, v90
	v_mul_f32_e32 v173, 0xbfb8aa3b, v91
	v_mul_f32_e32 v174, 0xbfb8aa3b, v92
	v_mul_f32_e32 v175, 0xbfb8aa3b, v93
	v_mul_f32_e32 v176, 0xbfb8aa3b, v94
	v_mul_f32_e32 v177, 0xbfb8aa3b, v95
	v_exp_f32_e32 v162, v162
	v_exp_f32_e32 v163, v163
	v_exp_f32_e32 v164, v164
	v_exp_f32_e32 v165, v165
	v_exp_f32_e32 v166, v166
	v_exp_f32_e32 v167, v167
	v_exp_f32_e32 v168, v168
	v_exp_f32_e32 v169, v169
	v_exp_f32_e32 v170, v170
	v_exp_f32_e32 v171, v171
	v_exp_f32_e32 v172, v172
	v_exp_f32_e32 v173, v173
	v_exp_f32_e32 v174, v174
	v_exp_f32_e32 v175, v175
	v_exp_f32_e32 v176, v176
	v_exp_f32_e32 v177, v177
	v_add_f32_e32 v162, 1.0, v162
	v_add_f32_e32 v163, 1.0, v163
	v_add_f32_e32 v164, 1.0, v164
	v_add_f32_e32 v165, 1.0, v165
	v_add_f32_e32 v166, 1.0, v166
	v_add_f32_e32 v167, 1.0, v167
	v_add_f32_e32 v168, 1.0, v168
	v_add_f32_e32 v169, 1.0, v169
	v_add_f32_e32 v170, 1.0, v170
	v_add_f32_e32 v171, 1.0, v171
	v_add_f32_e32 v172, 1.0, v172
	v_add_f32_e32 v173, 1.0, v173
	v_add_f32_e32 v174, 1.0, v174
	v_add_f32_e32 v175, 1.0, v175
	v_add_f32_e32 v176, 1.0, v176
	v_add_f32_e32 v177, 1.0, v177
	v_rcp_f32_e32 v162, v162
	v_rcp_f32_e32 v163, v163
	v_rcp_f32_e32 v164, v164
	v_rcp_f32_e32 v165, v165
	v_rcp_f32_e32 v166, v166
	v_rcp_f32_e32 v167, v167
	v_rcp_f32_e32 v168, v168
	v_rcp_f32_e32 v169, v169
	v_rcp_f32_e32 v170, v170
	v_rcp_f32_e32 v171, v171
	v_rcp_f32_e32 v172, v172
	v_rcp_f32_e32 v173, v173
	v_rcp_f32_e32 v174, v174
	v_rcp_f32_e32 v175, v175
	v_rcp_f32_e32 v176, v176
	v_rcp_f32_e32 v177, v177
	v_mul_f32_e32 v80, v80, v162
	v_mul_f32_e32 v81, v81, v163
	v_mul_f32_e32 v82, v82, v164
	v_mul_f32_e32 v83, v83, v165
	v_mul_f32_e32 v84, v84, v166
	v_mul_f32_e32 v85, v85, v167
	v_mul_f32_e32 v86, v86, v168
	v_mul_f32_e32 v87, v87, v169
	v_mul_f32_e32 v88, v88, v170
	v_mul_f32_e32 v89, v89, v171
	v_mul_f32_e32 v90, v90, v172
	v_mul_f32_e32 v91, v91, v173
	v_mul_f32_e32 v92, v92, v174
	v_mul_f32_e32 v93, v93, v175
	v_mul_f32_e32 v94, v94, v176
	v_mul_f32_e32 v95, v95, v177
	v_mul_f32_e32 v80, v64, v80
	v_mul_f32_e32 v81, v65, v81
	v_mul_f32_e32 v82, v66, v82
	v_mul_f32_e32 v83, v67, v83
	v_mul_f32_e32 v84, v68, v84
	v_mul_f32_e32 v85, v69, v85
	v_mul_f32_e32 v86, v70, v86
	v_mul_f32_e32 v87, v71, v87
	v_mul_f32_e32 v88, v72, v88
	v_mul_f32_e32 v89, v73, v89
	v_mul_f32_e32 v90, v74, v90
	v_mul_f32_e32 v91, v75, v91
	v_mul_f32_e32 v92, v76, v92
	v_mul_f32_e32 v93, v77, v93
	v_mul_f32_e32 v94, v78, v94
	v_mul_f32_e32 v95, v79, v95
	v_cvt_pk_bf16_f32 v80, v80, s0
	v_cvt_pk_bf16_f32 v81, v81, s0
	v_cvt_pk_bf16_f32 v82, v82, s0
	v_cvt_pk_bf16_f32 v83, v83, s0
	v_cvt_pk_bf16_f32 v84, v84, s0
	v_cvt_pk_bf16_f32 v85, v85, s0
	v_cvt_pk_bf16_f32 v86, v86, s0
	v_cvt_pk_bf16_f32 v87, v87, s0
	v_cvt_pk_bf16_f32 v88, v88, s0
	v_cvt_pk_bf16_f32 v89, v89, s0
	v_cvt_pk_bf16_f32 v90, v90, s0
	v_cvt_pk_bf16_f32 v91, v91, s0
	v_cvt_pk_bf16_f32 v92, v92, s0
	v_cvt_pk_bf16_f32 v93, v93, s0
	v_cvt_pk_bf16_f32 v94, v94, s0
	v_cvt_pk_bf16_f32 v95, v95, s0
	v_mul_f32_e32 v162, 0xbfb8aa3b, v48
	v_mul_f32_e32 v163, 0xbfb8aa3b, v49
	v_mul_f32_e32 v164, 0xbfb8aa3b, v50
	v_mul_f32_e32 v165, 0xbfb8aa3b, v51
	v_mul_f32_e32 v166, 0xbfb8aa3b, v52
	v_mul_f32_e32 v167, 0xbfb8aa3b, v53
	v_mul_f32_e32 v168, 0xbfb8aa3b, v54
	v_mul_f32_e32 v169, 0xbfb8aa3b, v55
	v_mul_f32_e32 v170, 0xbfb8aa3b, v56
	v_mul_f32_e32 v171, 0xbfb8aa3b, v57
	v_mul_f32_e32 v172, 0xbfb8aa3b, v58
	v_mul_f32_e32 v173, 0xbfb8aa3b, v59
	v_mul_f32_e32 v174, 0xbfb8aa3b, v60
	v_mul_f32_e32 v175, 0xbfb8aa3b, v61
	v_mul_f32_e32 v176, 0xbfb8aa3b, v62
	v_mul_f32_e32 v177, 0xbfb8aa3b, v63
	v_exp_f32_e32 v162, v162
	v_exp_f32_e32 v163, v163
	v_exp_f32_e32 v164, v164
	v_exp_f32_e32 v165, v165
	v_exp_f32_e32 v166, v166
	v_exp_f32_e32 v167, v167
	v_exp_f32_e32 v168, v168
	v_exp_f32_e32 v169, v169
	v_exp_f32_e32 v170, v170
	v_exp_f32_e32 v171, v171
	v_exp_f32_e32 v172, v172
	v_exp_f32_e32 v173, v173
	v_exp_f32_e32 v174, v174
	v_exp_f32_e32 v175, v175
	v_exp_f32_e32 v176, v176
	v_exp_f32_e32 v177, v177
	v_add_f32_e32 v162, 1.0, v162
	v_add_f32_e32 v163, 1.0, v163
	v_add_f32_e32 v164, 1.0, v164
	v_add_f32_e32 v165, 1.0, v165
	v_add_f32_e32 v166, 1.0, v166
	v_add_f32_e32 v167, 1.0, v167
	v_add_f32_e32 v168, 1.0, v168
	v_add_f32_e32 v169, 1.0, v169
	v_add_f32_e32 v170, 1.0, v170
	v_add_f32_e32 v171, 1.0, v171
	v_add_f32_e32 v172, 1.0, v172
	v_add_f32_e32 v173, 1.0, v173
	v_add_f32_e32 v174, 1.0, v174
	v_add_f32_e32 v175, 1.0, v175
	v_add_f32_e32 v176, 1.0, v176
	v_add_f32_e32 v177, 1.0, v177
	v_rcp_f32_e32 v162, v162
	v_rcp_f32_e32 v163, v163
	v_rcp_f32_e32 v164, v164
	v_rcp_f32_e32 v165, v165
	v_rcp_f32_e32 v166, v166
	v_rcp_f32_e32 v167, v167
	v_rcp_f32_e32 v168, v168
	v_rcp_f32_e32 v169, v169
	v_rcp_f32_e32 v170, v170
	v_rcp_f32_e32 v171, v171
	v_rcp_f32_e32 v172, v172
	v_rcp_f32_e32 v173, v173
	v_rcp_f32_e32 v174, v174
	v_rcp_f32_e32 v175, v175
	v_rcp_f32_e32 v176, v176
	v_rcp_f32_e32 v177, v177
	v_mul_f32_e32 v48, v48, v162
	v_mul_f32_e32 v49, v49, v163
	v_mul_f32_e32 v50, v50, v164
	v_mul_f32_e32 v51, v51, v165
	v_mul_f32_e32 v52, v52, v166
	v_mul_f32_e32 v53, v53, v167
	v_mul_f32_e32 v54, v54, v168
	v_mul_f32_e32 v55, v55, v169
	v_mul_f32_e32 v56, v56, v170
	v_mul_f32_e32 v57, v57, v171
	v_mul_f32_e32 v58, v58, v172
; DI float silu_f(float x) { return x * __builtin_amdgcn_rcpf(1.f + __expf(-x)); }
; template <int EPI, int MI>
; DI void gemm_tile(const GemmDesc& g, int tm, int tn, char* smem) {
;     ...
; #pragma unroll
;     for (int mi = 0; mi < MI; ++mi)
; #pragma unroll
;       for (int i = 0; i < 16; ++i) {
;         const int lrow = wm * (32 * MI) + mi * 32 + (i & 3) + 8 * (i >> 2) + 4 * hh;
;         es[lrow * 64 + wn * 32 + r] = f2bf(silu_f(acc[mi][0][i]) * acc[mi][1][i]);
;       }
;     __syncthreads();
	v_mul_f32_e32 v59, v59, v173
	v_mul_f32_e32 v60, v60, v174
	v_mul_f32_e32 v61, v61, v175
	v_mul_f32_e32 v62, v62, v176
	v_mul_f32_e32 v63, v63, v177
	v_mul_f32_e32 v48, v32, v48
	v_mul_f32_e32 v49, v33, v49
	v_mul_f32_e32 v50, v34, v50
	v_mul_f32_e32 v51, v35, v51
	v_mul_f32_e32 v52, v36, v52
	v_mul_f32_e32 v53, v37, v53
	v_mul_f32_e32 v54, v38, v54
	v_mul_f32_e32 v55, v39, v55
	v_mul_f32_e32 v56, v40, v56
	v_mul_f32_e32 v57, v41, v57
	v_mul_f32_e32 v58, v42, v58
	v_mul_f32_e32 v59, v43, v59
	v_mul_f32_e32 v60, v44, v60
	v_mul_f32_e32 v61, v45, v61
	v_mul_f32_e32 v62, v46, v62
	v_mul_f32_e32 v63, v47, v63
	v_cvt_pk_bf16_f32 v48, v48, s0
	v_cvt_pk_bf16_f32 v49, v49, s0
	v_cvt_pk_bf16_f32 v50, v50, s0
	v_cvt_pk_bf16_f32 v51, v51, s0
	v_cvt_pk_bf16_f32 v52, v52, s0
	v_cvt_pk_bf16_f32 v53, v53, s0
	v_cvt_pk_bf16_f32 v54, v54, s0
	v_cvt_pk_bf16_f32 v55, v55, s0
	v_cvt_pk_bf16_f32 v56, v56, s0
	v_cvt_pk_bf16_f32 v57, v57, s0
	v_cvt_pk_bf16_f32 v58, v58, s0
	v_cvt_pk_bf16_f32 v59, v59, s0
	v_cvt_pk_bf16_f32 v60, v60, s0
	v_cvt_pk_bf16_f32 v61, v61, s0
	v_cvt_pk_bf16_f32 v62, v62, s0
	v_cvt_pk_bf16_f32 v63, v63, s0
	v_mul_f32_e32 v162, 0xbfb8aa3b, v16
	v_mul_f32_e32 v163, 0xbfb8aa3b, v17
	v_mul_f32_e32 v164, 0xbfb8aa3b, v18
	v_mul_f32_e32 v165, 0xbfb8aa3b, v19
	v_mul_f32_e32 v166, 0xbfb8aa3b, v20
	v_mul_f32_e32 v167, 0xbfb8aa3b, v21
	v_mul_f32_e32 v168, 0xbfb8aa3b, v22
	v_mul_f32_e32 v169, 0xbfb8aa3b, v23
	v_mul_f32_e32 v170, 0xbfb8aa3b, v24
	v_mul_f32_e32 v171, 0xbfb8aa3b, v25
	v_mul_f32_e32 v172, 0xbfb8aa3b, v26
	v_mul_f32_e32 v173, 0xbfb8aa3b, v27
	v_mul_f32_e32 v174, 0xbfb8aa3b, v28
	v_mul_f32_e32 v175, 0xbfb8aa3b, v29
	v_mul_f32_e32 v176, 0xbfb8aa3b, v30
	v_mul_f32_e32 v177, 0xbfb8aa3b, v31
	v_exp_f32_e32 v162, v162
	v_exp_f32_e32 v163, v163
	v_exp_f32_e32 v164, v164
	v_exp_f32_e32 v165, v165
	v_exp_f32_e32 v166, v166
	v_exp_f32_e32 v167, v167
	v_exp_f32_e32 v168, v168
	v_exp_f32_e32 v169, v169
	v_exp_f32_e32 v170, v170
	v_exp_f32_e32 v171, v171
	v_exp_f32_e32 v172, v172
	v_exp_f32_e32 v173, v173
	v_exp_f32_e32 v174, v174
	v_exp_f32_e32 v175, v175
	v_exp_f32_e32 v176, v176
	v_exp_f32_e32 v177, v177
	v_add_f32_e32 v162, 1.0, v162
	v_add_f32_e32 v163, 1.0, v163
	v_add_f32_e32 v164, 1.0, v164
	v_add_f32_e32 v165, 1.0, v165
	v_add_f32_e32 v166, 1.0, v166
	v_add_f32_e32 v167, 1.0, v167
	v_add_f32_e32 v168, 1.0, v168
	v_add_f32_e32 v169, 1.0, v169
	v_add_f32_e32 v170, 1.0, v170
	v_add_f32_e32 v171, 1.0, v171
	v_add_f32_e32 v172, 1.0, v172
	v_add_f32_e32 v173, 1.0, v173
	v_add_f32_e32 v174, 1.0, v174
	v_add_f32_e32 v175, 1.0, v175
	v_add_f32_e32 v176, 1.0, v176
	v_add_f32_e32 v177, 1.0, v177
	v_rcp_f32_e32 v162, v162
	v_rcp_f32_e32 v163, v163
	v_rcp_f32_e32 v164, v164
	v_rcp_f32_e32 v165, v165
	v_rcp_f32_e32 v166, v166
	v_rcp_f32_e32 v167, v167
	v_rcp_f32_e32 v168, v168
	v_rcp_f32_e32 v169, v169
	v_rcp_f32_e32 v170, v170
	v_rcp_f32_e32 v171, v171
	v_rcp_f32_e32 v172, v172
	v_rcp_f32_e32 v173, v173
	v_rcp_f32_e32 v174, v174
	v_rcp_f32_e32 v175, v175
	v_rcp_f32_e32 v176, v176
	v_rcp_f32_e32 v177, v177
	v_mul_f32_e32 v16, v16, v162
	v_mul_f32_e32 v17, v17, v163
	v_mul_f32_e32 v18, v18, v164
	v_mul_f32_e32 v19, v19, v165
	v_mul_f32_e32 v20, v20, v166
	v_mul_f32_e32 v21, v21, v167
	v_mul_f32_e32 v22, v22, v168
	v_mul_f32_e32 v23, v23, v169
	v_mul_f32_e32 v24, v24, v170
	v_mul_f32_e32 v25, v25, v171
	v_mul_f32_e32 v26, v26, v172
	v_mul_f32_e32 v27, v27, v173
	v_mul_f32_e32 v28, v28, v174
	v_mul_f32_e32 v29, v29, v175
	v_mul_f32_e32 v30, v30, v176
	v_mul_f32_e32 v31, v31, v177
	v_mul_f32_e32 v16, v0, v16
	v_mul_f32_e32 v17, v1, v17
	v_mul_f32_e32 v18, v2, v18
	v_mul_f32_e32 v19, v3, v19
	v_mul_f32_e32 v20, v4, v20
	v_mul_f32_e32 v21, v5, v21
	v_mul_f32_e32 v22, v6, v22
	v_mul_f32_e32 v23, v7, v23
	v_mul_f32_e32 v24, v8, v24
	v_mul_f32_e32 v25, v9, v25
	v_mul_f32_e32 v26, v10, v26
	v_mul_f32_e32 v27, v11, v27
	v_mul_f32_e32 v28, v12, v28
	v_mul_f32_e32 v29, v13, v29
	v_mul_f32_e32 v30, v14, v30
	v_mul_f32_e32 v31, v15, v31
	v_cvt_pk_bf16_f32 v16, v16, s0
	v_cvt_pk_bf16_f32 v17, v17, s0
	v_cvt_pk_bf16_f32 v18, v18, s0
	v_cvt_pk_bf16_f32 v19, v19, s0
	v_cvt_pk_bf16_f32 v20, v20, s0
	v_cvt_pk_bf16_f32 v21, v21, s0
	v_cvt_pk_bf16_f32 v22, v22, s0
	v_cvt_pk_bf16_f32 v23, v23, s0
	v_cvt_pk_bf16_f32 v24, v24, s0
	v_cvt_pk_bf16_f32 v25, v25, s0
	v_cvt_pk_bf16_f32 v26, v26, s0
	v_cvt_pk_bf16_f32 v27, v27, s0
	v_cvt_pk_bf16_f32 v28, v28, s0
	v_cvt_pk_bf16_f32 v29, v29, s0
	v_cvt_pk_bf16_f32 v30, v30, s0
	v_cvt_pk_bf16_f32 v31, v31, s0
	v_lshlrev_b32_e32 v99, 9, v122
	v_lshlrev_b32_e32 v100, 6, v123
	v_add3_u32 v99, 0, v99, v100
	v_lshlrev_b32_e32 v100, 1, v121
	v_readlane_b32 s16, v221, 5
	v_readlane_b32 s17, v221, 6
	s_movk_i32 s0, 0x3000
	v_mul_lo_u32 v64, v120, s0
	v_add3_u32 v64, v99, v100, v64
	s_movk_i32 s15, 0x1600
	v_lshlrev_b32_e32 v4, 4, v115
	v_mov_b32_e32 v5, v96
	v_mov_b64_e32 v[6:7], s[16:17]
	v_mad_i64_i32 v[8:9], s[16:17], v98, s15, v[6:7]
	v_add_u32_e32 v10, 0, v4
	v_lshl_add_u32 v0, v97, 7, v10
	ds_write_b16 v64, v80
	ds_write_b16 v64, v81 offset:128
	ds_write_b16 v64, v82 offset:256
	ds_write_b16 v64, v83 offset:384
	ds_write_b16 v64, v84 offset:1024
	ds_write_b16 v64, v85 offset:1152
	ds_write_b16 v64, v86 offset:1280
	ds_write_b16 v64, v87 offset:1408
	ds_write_b16 v64, v88 offset:2048
	ds_write_b16 v64, v89 offset:2176
	ds_write_b16 v64, v90 offset:2304
	ds_write_b16 v64, v91 offset:2432
	ds_write_b16 v64, v92 offset:3072
	ds_write_b16 v64, v93 offset:3200
	ds_write_b16 v64, v94 offset:3328
	ds_write_b16 v64, v95 offset:3456
	ds_write_b16 v64, v48 offset:4096
	ds_write_b16 v64, v49 offset:4224
	ds_write_b16 v64, v50 offset:4352
	ds_write_b16 v64, v51 offset:4480
	ds_write_b16 v64, v52 offset:5120
	ds_write_b16 v64, v53 offset:5248
	ds_write_b16 v64, v54 offset:5376
	ds_write_b16 v64, v55 offset:5504
	ds_write_b16 v64, v56 offset:6144
	ds_write_b16 v64, v57 offset:6272
	ds_write_b16 v64, v58 offset:6400
	ds_write_b16 v64, v59 offset:6528
	ds_write_b16 v64, v60 offset:7168
	ds_write_b16 v64, v61 offset:7296
	ds_write_b16 v64, v62 offset:7424
	ds_write_b16 v64, v63 offset:7552
	ds_write_b16 v64, v16 offset:8192
	ds_write_b16 v64, v17 offset:8320
	ds_write_b16 v64, v18 offset:8448
	ds_write_b16 v64, v19 offset:8576
	ds_write_b16 v64, v20 offset:9216
	ds_write_b16 v64, v21 offset:9344
	ds_write_b16 v64, v22 offset:9472
	ds_write_b16 v64, v23 offset:9600
	ds_write_b16 v64, v24 offset:10240
	ds_write_b16 v64, v25 offset:10368
	ds_write_b16 v64, v26 offset:10496
	ds_write_b16 v64, v27 offset:10624
	ds_write_b16 v64, v28 offset:11264
	ds_write_b16 v64, v29 offset:11392
	ds_write_b16 v64, v30 offset:11520
	ds_write_b16 v64, v31 offset:11648
	s_waitcnt lgkmcnt(0)
	s_barrier
; template <int EPI, int MI>
; DI void gemm_tile(const GemmDesc& g, int tm, int tn, char* smem) {
;     ...
; #pragma unroll
;     for (int j = 0; j < 2 * MI; ++j) {
;       const int lrow = (tid >> 3) + 32 * j, ch = tid & 7;
;       const u32x4 v = *(const u32x4*)(es + lrow * 64 + ch * 8);
;       *(u32x4*)(g.o16 + (size_t)(m0 + lrow) * g.ldo + (n0 >> 1) + ch * 8) = v;
;     }
;     __syncthreads();
	s_lshl_b32 s0, s39, 6
	ds_read_b128 v[0:3], v0
	s_ashr_i32 s1, s0, 31
	s_lshl_b64 s[0:1], s[0:1], 1
	v_lshl_add_u64 v[8:9], v[8:9], 0, s[0:1]
	v_lshl_add_u64 v[8:9], v[8:9], 0, v[4:5]
	s_waitcnt lgkmcnt(0)
	global_store_dwordx4 v[8:9], v[0:3], off
	v_add_u32_e32 v8, 32, v97
	s_nop 0
	v_lshl_add_u32 v0, v8, 7, v10
	ds_read_b128 v[0:3], v0
	v_add_u32_e32 v8, s38, v8
	v_mad_i64_i32 v[8:9], s[16:17], v8, s15, v[6:7]
	v_lshl_add_u64 v[8:9], v[8:9], 0, s[0:1]
	v_lshl_add_u64 v[8:9], v[8:9], 0, v[4:5]
	s_waitcnt lgkmcnt(0)
	global_store_dwordx4 v[8:9], v[0:3], off
	v_add_u32_e32 v8, 64, v97
	s_nop 0
	v_lshl_add_u32 v0, v8, 7, v10
	ds_read_b128 v[0:3], v0
	v_add_u32_e32 v8, s38, v8
	v_mad_i64_i32 v[8:9], s[16:17], v8, s15, v[6:7]
	v_lshl_add_u64 v[8:9], v[8:9], 0, s[0:1]
	v_lshl_add_u64 v[8:9], v[8:9], 0, v[4:5]
	s_waitcnt lgkmcnt(0)
	global_store_dwordx4 v[8:9], v[0:3], off
	v_add_u32_e32 v8, 0x60, v97
	s_nop 0
	v_lshl_add_u32 v0, v8, 7, v10
	ds_read_b128 v[0:3], v0
	v_add_u32_e32 v8, s38, v8
	v_mad_i64_i32 v[8:9], s[16:17], v8, s15, v[6:7]
	v_lshl_add_u64 v[8:9], v[8:9], 0, s[0:1]
	v_lshl_add_u64 v[8:9], v[8:9], 0, v[4:5]
	s_waitcnt lgkmcnt(0)
	global_store_dwordx4 v[8:9], v[0:3], off
	v_add_u32_e32 v8, 0x80, v97
	s_nop 0
	v_lshl_add_u32 v0, v8, 7, v10
	ds_read_b128 v[0:3], v0
	v_add_u32_e32 v8, s38, v8
	v_mad_i64_i32 v[8:9], s[16:17], v8, s15, v[6:7]
	v_lshl_add_u64 v[8:9], v[8:9], 0, s[0:1]
	v_lshl_add_u64 v[8:9], v[8:9], 0, v[4:5]
	s_waitcnt lgkmcnt(0)
	global_store_dwordx4 v[8:9], v[0:3], off
	v_add_u32_e32 v8, 0xa0, v97
	s_nop 0
	v_lshl_add_u32 v0, v8, 7, v10
	v_add_u32_e32 v8, s38, v8
	ds_read_b128 v[0:3], v0
	v_mad_i64_i32 v[6:7], s[16:17], v8, s15, v[6:7]
	v_lshl_add_u64 v[6:7], v[6:7], 0, s[0:1]
	v_readlane_b32 s0, v218, 38
	s_add_i32 s5, s5, s0
	v_readlane_b32 s0, v218, 31
	s_add_i32 s4, s4, s0
	v_readlane_b32 s0, v221, 7
	v_lshl_add_u64 v[4:5], v[6:7], 0, v[4:5]
	s_cmp_lt_i32 s5, s0
	s_waitcnt lgkmcnt(0)
	global_store_dwordx4 v[4:5], v[0:3], off
	s_barrier
	s_cbranch_scc0 .LBB0_198
.LBB0_202:
	s_abs_i32 s1, s5
	v_readlane_b32 s15, v219, 45
	s_mul_hi_u32 s15, s1, s15
	v_readlane_b32 s18, v219, 44
	s_mul_i32 s16, s15, s18
	s_sub_i32 s1, s1, s16
	s_ashr_i32 s0, s5, 31
	s_add_i32 s16, s15, 1
	s_sub_i32 s17, s1, s18
	s_cmp_ge_u32 s1, s18
	s_cselect_b32 s15, s16, s15
	s_cselect_b32 s1, s17, s1
	s_add_i32 s16, s15, 1
	s_cmp_ge_u32 s1, s18
	s_cselect_b32 s1, s16, s15
	s_xor_b32 s1, s1, s0
	s_sub_i32 s15, s1, s0
	s_mul_i32 s16, s15, s18
	s_sub_i32 s16, s5, s16
	s_abs_i32 s18, s16
	v_readlane_b32 s19, v219, 46
	s_mul_hi_u32 s19, s18, s19
	v_readlane_b32 s42, v218, 32
	s_mul_i32 s38, s19, s42
	s_sub_i32 s18, s18, s38
	s_ashr_i32 s17, s16, 31
	s_add_i32 s38, s19, 1
	s_sub_i32 s39, s18, s42
	s_cmp_ge_u32 s18, s42
	s_cselect_b32 s19, s38, s19
	s_cselect_b32 s18, s39, s18
	s_add_i32 s38, s19, 1
	s_cmp_ge_u32 s18, s42
	s_cselect_b32 s18, s38, s19
	s_xor_b32 s18, s18, s17
	s_sub_i32 s39, s18, s17
	s_sub_i32 s15, s15, s39
	v_mov_b32_e32 v4, v132
	s_mul_i32 s15, s15, s42
	s_add_i32 s16, s16, s54
	s_add_i32 s38, s16, s15
	v_ashrrev_i32_e32 v97, 3, v4
	v_ashrrev_i32_e32 v120, 7, v4
	v_bfe_u32 v0, v4, 6, 2
	v_xor_b32_e32 v1, v97, v4
	s_mulk_i32 s38, 0xc0
	v_and_b32_e32 v121, 31, v4
	v_bitop3_b32 v2, v1, v0, 7 bitop3:0x6c
	v_mul_lo_u32 v0, v120, s6
	v_and_b32_e32 v115, 7, v4
	v_or_b32_e32 v5, v0, v121
	v_lshrrev_b32_e32 v0, 3, v4
	s_waitcnt vmcnt(10)
	v_add_u32_e32 v98, s38, v97
	v_bfe_u32 v122, v4, 5, 1
	v_bitop3_b32 v0, v0, v115, 3 bitop3:0x6c
	v_ashrrev_i32_e32 v99, 31, v98
	v_xor_b32_e32 v6, v0, v122
	v_lshlrev_b64 v[0:1], 11, v[98:99]
	v_readlane_b32 s42, v223, 59
	v_lshlrev_b32_e32 v99, 4, v4
	v_readlane_b32 s43, v223, 60
	v_lshlrev_b32_e32 v100, 4, v2
	v_lshl_add_u32 v2, s39, 7, v97
	v_add_u32_e32 v124, 0, v99
	v_lshl_add_u64 v[0:1], s[42:43], 0, v[0:1]
	v_mov_b32_e32 v101, v96
	v_ashrrev_i32_e32 v3, 31, v2
	v_readfirstlane_b32 s15, v124
	v_add_u32_e32 v125, 0x1000, v124
	v_lshl_add_u64 v[0:1], v[0:1], 0, v[100:101]
	v_lshlrev_b64 v[2:3], 11, v[2:3]
	s_mov_b32 m0, s15
	s_mov_b64 s[42:43], 0x10000
	v_readfirstlane_b32 s15, v125
	v_add_u32_e32 v126, 0x2000, v124
	s_waitcnt vmcnt(9)
	v_lshl_add_u64 v[102:103], s[70:71], 0, v[2:3]
	global_load_lds_dwordx4 v[0:1], off
	v_lshl_add_u64 v[2:3], v[0:1], 0, s[42:43]
	s_mov_b32 m0, s15
	s_mov_b64 s[44:45], 0x20000
	v_readfirstlane_b32 s15, v126
	v_add_u32_e32 v127, 0x3000, v124
	global_load_lds_dwordx4 v[2:3], off
	v_lshl_add_u64 v[2:3], v[0:1], 0, s[44:45]
	s_mov_b32 m0, s15
	s_mov_b64 s[46:47], 0x30000
	v_readfirstlane_b32 s15, v127
	v_add_u32_e32 v128, 0x4000, v124
	global_load_lds_dwordx4 v[2:3], off
	v_lshl_add_u64 v[2:3], v[0:1], 0, s[46:47]
	s_mov_b32 m0, s15
	s_mov_b64 s[52:53], 0x40000
	v_readfirstlane_b32 s15, v128
	v_add_u32_e32 v129, 0x5000, v124
	global_load_lds_dwordx4 v[2:3], off
	v_lshl_add_u64 v[2:3], v[0:1], 0, s[52:53]
	s_mov_b32 m0, s15
	s_mov_b64 s[52:53], 0x50000
	v_readfirstlane_b32 s15, v129
	v_add_u32_e32 v130, 0xc000, v124
	global_load_lds_dwordx4 v[2:3], off
	v_lshl_add_u64 v[0:1], v[0:1], 0, s[52:53]
	s_mov_b32 m0, s15
	v_readfirstlane_b32 s15, v130
	v_add_u32_e32 v131, 0xd000, v124
	global_load_lds_dwordx4 v[0:1], off
	v_lshl_add_u64 v[0:1], v[102:103], 0, v[100:101]
	s_mov_b32 m0, s15
	v_readfirstlane_b32 s15, v131
	v_add_u32_e32 v153, 0xe000, v124
	global_load_lds_dwordx4 v[0:1], off
	v_lshl_add_u64 v[2:3], v[0:1], 0, s[42:43]
	s_mov_b32 m0, s15
	v_readfirstlane_b32 s15, v153
	v_add_u32_e32 v154, 0xf000, v124
	global_load_lds_dwordx4 v[2:3], off
	v_lshl_add_u64 v[2:3], v[0:1], 0, s[44:45]
	s_mov_b32 m0, s15
	v_readfirstlane_b32 s15, v154
	global_load_lds_dwordx4 v[2:3], off
	v_lshl_add_u64 v[0:1], v[0:1], 0, s[46:47]
	s_mov_b32 m0, s15
	s_mul_i32 s0, s0, 43
	global_load_lds_dwordx4 v[0:1], off
	s_add_i32 s17, s17, s0
	s_sub_i32 s0, s17, s18
	s_mul_i32 s1, s1, 43
	s_sub_i32 s0, s0, s1
	v_readlane_b32 s1, v218, 33
	v_bfe_u32 v123, v4, 6, 1
	v_lshlrev_b32_e32 v0, 7, v121
	s_mul_i32 s0, s1, s0
	v_lshl_or_b32 v0, v123, 13, v0
	s_add_i32 s0, s0, s4
	v_add_u32_e32 v156, 0, v0
	v_add_u32_e32 v158, s10, v0
	v_add_u32_e32 v0, s0, v97
	v_ashrrev_i32_e32 v1, 31, v0
	s_waitcnt vmcnt(0)
; template <int EPI, int MI>
; DI void gemm_tile(const GemmDesc& g, int tm, int tn, char* smem) {
;     ...
;   const int nk = g.K >> 6;
;   f32x16 acc[MI][2];
; #pragma unroll
;   for (int a = 0; a < MI; ++a)
; #pragma unroll
;     for (int b = 0; b < 2; ++b)
; #pragma unroll
;       for (int i = 0; i < 16; ++i) acc[a][b][i] = 0.f;
;   const int srow = tid >> 3;
;   const int schunk = (tid & 7) ^ ((srow & 7) ^ ((srow >> 3) & 3));
;     ...
;   G_GLDS(0, 0);
;   asm volatile("s_waitcnt vmcnt(0)" ::: "memory");
;   __syncthreads();
;   for (int kt = 0; kt < nk; kt += 2) {
;     if (kt + 1 < nk) G_GLDS(kt + 1, 1);
;     G_COMPUTE(0);
;     asm volatile("s_waitcnt vmcnt(0)" ::: "memory");
;     __syncthreads();
;     if (kt + 1 < nk) {
;       if (kt + 2 < nk) G_GLDS(kt + 2, 0);
;       G_COMPUTE(1);
;       asm volatile("s_waitcnt vmcnt(0)" ::: "memory");
;       __syncthreads();
;     }
;   }
	v_lshlrev_b64 v[0:1], 11, v[0:1]
	v_lshlrev_b32_e32 v157, 4, v6
	v_lshl_add_u64 v[104:105], s[70:71], 0, v[0:1]
	v_mov_b32_e32 v0, 0
	v_lshl_add_u32 v155, v5, 7, 0
	s_mov_b32 s15, 0
	v_mov_b32_e32 v1, v0
	v_mov_b32_e32 v2, v0
	v_mov_b32_e32 v3, v0
	v_mov_b32_e32 v4, v0
	v_mov_b32_e32 v5, v0
	v_mov_b32_e32 v6, v0
	v_mov_b32_e32 v7, v0
	v_mov_b32_e32 v8, v0
	v_mov_b32_e32 v9, v0
	v_mov_b32_e32 v10, v0
	v_mov_b32_e32 v11, v0
	v_mov_b32_e32 v12, v0
	v_mov_b32_e32 v13, v0
	v_mov_b32_e32 v14, v0
	v_mov_b32_e32 v15, v0
	v_mov_b32_e32 v16, v0
	v_mov_b32_e32 v17, v0
	v_mov_b32_e32 v18, v0
	v_mov_b32_e32 v19, v0
	v_mov_b32_e32 v20, v0
	v_mov_b32_e32 v21, v0
	v_mov_b32_e32 v22, v0
	v_mov_b32_e32 v23, v0
	v_mov_b32_e32 v24, v0
	v_mov_b32_e32 v25, v0
	v_mov_b32_e32 v26, v0
	v_mov_b32_e32 v27, v0
	v_mov_b32_e32 v28, v0
	v_mov_b32_e32 v29, v0
	v_mov_b32_e32 v30, v0
	v_mov_b32_e32 v31, v0
	v_mov_b32_e32 v32, v0
	v_mov_b32_e32 v33, v0
	v_mov_b32_e32 v34, v0
	v_mov_b32_e32 v35, v0
	v_mov_b32_e32 v36, v0
	v_mov_b32_e32 v37, v0
	v_mov_b32_e32 v38, v0
	v_mov_b32_e32 v39, v0
	v_mov_b32_e32 v40, v0
	v_mov_b32_e32 v41, v0
	v_mov_b32_e32 v42, v0
	v_mov_b32_e32 v43, v0
	v_mov_b32_e32 v44, v0
	v_mov_b32_e32 v45, v0
	v_mov_b32_e32 v46, v0
	v_mov_b32_e32 v47, v0
	v_mov_b32_e32 v48, v0
	s_waitcnt vmcnt(0)
	v_mov_b32_e32 v49, v0
	v_mov_b32_e32 v50, v0
	v_mov_b32_e32 v51, v0
	v_mov_b32_e32 v52, v0
	v_mov_b32_e32 v53, v0
	v_mov_b32_e32 v54, v0
	v_mov_b32_e32 v55, v0
	v_mov_b32_e32 v56, v0
	v_mov_b32_e32 v57, v0
	v_mov_b32_e32 v58, v0
	v_mov_b32_e32 v59, v0
	v_mov_b32_e32 v60, v0
	v_mov_b32_e32 v61, v0
	v_mov_b32_e32 v62, v0
	v_mov_b32_e32 v63, v0
	v_mov_b32_e32 v64, v0
	v_mov_b32_e32 v65, v0
	v_mov_b32_e32 v66, v0
	v_mov_b32_e32 v67, v0
	v_mov_b32_e32 v68, v0
	v_mov_b32_e32 v69, v0
	v_mov_b32_e32 v70, v0
	v_mov_b32_e32 v71, v0
	v_mov_b32_e32 v72, v0
	v_mov_b32_e32 v73, v0
	v_mov_b32_e32 v74, v0
	v_mov_b32_e32 v75, v0
	v_mov_b32_e32 v76, v0
	v_mov_b32_e32 v77, v0
	v_mov_b32_e32 v78, v0
	v_mov_b32_e32 v79, v0
	v_mov_b32_e32 v80, v0
	v_mov_b32_e32 v81, v0
	v_mov_b32_e32 v82, v0
	v_mov_b32_e32 v83, v0
	v_mov_b32_e32 v84, v0
	v_mov_b32_e32 v85, v0
	v_mov_b32_e32 v86, v0
	v_mov_b32_e32 v87, v0
	v_mov_b32_e32 v88, v0
	v_mov_b32_e32 v89, v0
	v_mov_b32_e32 v90, v0
	v_mov_b32_e32 v91, v0
	v_mov_b32_e32 v92, v0
	v_mov_b32_e32 v93, v0
	v_mov_b32_e32 v94, v0
	v_mov_b32_e32 v95, v0
	v_xor_b32_e32 v159, 32, v157
	v_xor_b32_e32 v160, 64, v157
	v_xor_b32_e32 v161, 0x60, v157
	s_mov_b64 s[18:19], 0x80
	s_mov_b64 s[42:43], 0x10080
	v_add_u32_e32 v162, v155, v157
	v_add_u32_e32 v163, v155, v159
	v_add_u32_e32 v164, v155, v160
	v_add_u32_e32 v165, v155, v161
	v_add_u32_e32 v166, v156, v157
	v_add_u32_e32 v167, v156, v159
	v_add_u32_e32 v168, v156, v160
	v_add_u32_e32 v169, v156, v161
	v_add_u32_e32 v170, v158, v157
	v_add_u32_e32 v171, v158, v159
	v_add_u32_e32 v172, v158, v160
	v_add_u32_e32 v173, v158, v161
	v_lshl_add_u64 v[174:175], v[104:105], 0, v[100:101]
	v_lshl_add_u64 v[176:177], v[102:103], 0, v[100:101]
	v_readfirstlane_b32 s100, v124
	s_movk_i32 s16, 0xc0
	v_cmp_gt_u32_e32 vcc, s16, v132
	v_add_u32_e32 v106, s38, v132
	s_lshl_b32 s17, s39, 7
	s_sub_u32 s16, s17, s16
	v_add_u32_e32 v107, s16, v132
	v_cndmask_b32_e32 v106, v107, v106, vcc
	v_lshlrev_b32_e32 v106, 11, v106
	v_mov_b32_e32 v107, 0x3472000
	v_cndmask_b32_e32 v107, 0, v107, vcc
	v_add_u32_e32 v106, v106, v107
	v_mov_b32_e32 v107, 0
	v_lshl_add_u64 v[252:253], s[70:71], 0, v[106:107]
	v_lshrrev_b32_e32 v106, 2, v132
	s_add_u32 s17, s17, 64
	v_add_u32_e32 v106, s17, v106
	v_lshlrev_b32_e32 v106, 11, v106
	v_lshl_add_u64 v[108:109], s[70:71], 0, v[106:107]
	s_waitcnt vmcnt(0) lgkmcnt(0)
	s_barrier
	ds_read_b128 v[236:239], v166 offset:49152
	ds_read_b128 v[240:243], v166 offset:53248
	ds_read_b128 v[224:227], v162
	ds_read_b128 v[228:231], v162 offset:4096
	s_mov_b32 s15, 0
.Lga_loop:
	ds_read_b128 v[232:235], v162 offset:8192
	s_waitcnt lgkmcnt(2)
	v_mfma_f32_32x32x16_bf16 v[80:95], v[224:227], v[236:239], v[80:95]
	v_mfma_f32_32x32x16_bf16 v[64:79], v[224:227], v[240:243], v[64:79]
	s_add_u32 m0, s100, 0x6000
	v_lshl_add_u64 v[106:107], v[174:175], 0, s[96:97]
	global_load_lds_dwordx4 v[106:107], off
	ds_read_b128 v[244:247], v167 offset:49152
	ds_read_b128 v[248:251], v167 offset:53248
	ds_read_b128 v[224:227], v163
	s_waitcnt lgkmcnt(4)
	v_mfma_f32_32x32x16_bf16 v[48:63], v[228:231], v[236:239], v[48:63]
	v_mfma_f32_32x32x16_bf16 v[32:47], v[228:231], v[240:243], v[32:47]
	s_add_u32 m0, s100, 0x7000
	v_lshl_add_u64 v[106:107], v[174:175], 0, s[50:51]
	global_load_lds_dwordx4 v[106:107], off
	ds_read_b128 v[228:231], v163 offset:4096
	s_waitcnt lgkmcnt(4)
	v_mfma_f32_32x32x16_bf16 v[16:31], v[232:235], v[236:239], v[16:31]
	v_mfma_f32_32x32x16_bf16 v[0:15], v[232:235], v[240:243], v[0:15]
	s_add_u32 m0, s100, 0x8000
	v_lshl_add_u64 v[106:107], v[174:175], 0, s[24:25]
	global_load_lds_dwordx4 v[106:107], off
	ds_read_b128 v[232:235], v163 offset:8192
	s_waitcnt lgkmcnt(2)
	v_mfma_f32_32x32x16_bf16 v[80:95], v[224:227], v[244:247], v[80:95]
	v_mfma_f32_32x32x16_bf16 v[64:79], v[224:227], v[248:251], v[64:79]
	s_add_u32 m0, s100, 0x9000
	v_lshl_add_u64 v[106:107], v[174:175], 0, s[26:27]
	global_load_lds_dwordx4 v[106:107], off
	ds_read_b128 v[236:239], v168 offset:49152
	ds_read_b128 v[240:243], v168 offset:53248
	ds_read_b128 v[224:227], v164
	s_waitcnt lgkmcnt(4)
	v_mfma_f32_32x32x16_bf16 v[48:63], v[228:231], v[244:247], v[48:63]
	v_mfma_f32_32x32x16_bf16 v[32:47], v[228:231], v[248:251], v[32:47]
	s_add_u32 m0, s100, 0xa000
	v_lshl_add_u64 v[106:107], v[174:175], 0, s[28:29]
	global_load_lds_dwordx4 v[106:107], off
	ds_read_b128 v[228:231], v164 offset:4096
	s_waitcnt lgkmcnt(4)
; template <int EPI, int MI>
; DI void gemm_tile(const GemmDesc& g, int tm, int tn, char* smem) {
;     ...
;   for (int kt = 0; kt < nk; kt += 2) {
;     if (kt + 1 < nk) G_GLDS(kt + 1, 1);
;     G_COMPUTE(0);
;     asm volatile("s_waitcnt vmcnt(0)" ::: "memory");
;     __syncthreads();
;     if (kt + 1 < nk) {
;       if (kt + 2 < nk) G_GLDS(kt + 2, 0);
;       G_COMPUTE(1);
;       asm volatile("s_waitcnt vmcnt(0)" ::: "memory");
;       __syncthreads();
;     }
;   }
	v_mfma_f32_32x32x16_bf16 v[16:31], v[232:235], v[244:247], v[16:31]
	v_mfma_f32_32x32x16_bf16 v[0:15], v[232:235], v[248:251], v[0:15]
	s_add_u32 m0, s100, 0xb000
	v_lshl_add_u64 v[106:107], v[174:175], 0, s[30:31]
	global_load_lds_dwordx4 v[106:107], off
	v_lshl_add_u64 v[174:175], v[174:175], 0, s[18:19]
	ds_read_b128 v[232:235], v164 offset:8192
	s_waitcnt lgkmcnt(2)
	v_mfma_f32_32x32x16_bf16 v[80:95], v[224:227], v[236:239], v[80:95]
	v_mfma_f32_32x32x16_bf16 v[64:79], v[224:227], v[240:243], v[64:79]
	s_add_u32 m0, s100, 0x10000
	v_lshl_add_u64 v[106:107], v[176:177], 0, s[18:19]
	global_load_lds_dwordx4 v[106:107], off
	ds_read_b128 v[244:247], v169 offset:49152
	ds_read_b128 v[248:251], v169 offset:53248
	ds_read_b128 v[224:227], v165
	s_waitcnt lgkmcnt(4)
	v_mfma_f32_32x32x16_bf16 v[48:63], v[228:231], v[236:239], v[48:63]
	v_mfma_f32_32x32x16_bf16 v[32:47], v[228:231], v[240:243], v[32:47]
	s_add_u32 m0, s100, 0x11000
	v_lshl_add_u64 v[106:107], v[176:177], 0, s[42:43]
	global_load_lds_dwordx4 v[106:107], off
	ds_read_b128 v[228:231], v165 offset:4096
	s_waitcnt lgkmcnt(4)
	v_mfma_f32_32x32x16_bf16 v[16:31], v[232:235], v[236:239], v[16:31]
	v_mfma_f32_32x32x16_bf16 v[0:15], v[232:235], v[240:243], v[0:15]
	s_mov_b64 s[16:17], 0x20080
	s_add_u32 m0, s100, 0x12000
	v_lshl_add_u64 v[106:107], v[176:177], 0, s[16:17]
	global_load_lds_dwordx4 v[106:107], off
	ds_read_b128 v[232:235], v165 offset:8192
	s_waitcnt lgkmcnt(2)
	v_mfma_f32_32x32x16_bf16 v[80:95], v[224:227], v[244:247], v[80:95]
	v_mfma_f32_32x32x16_bf16 v[64:79], v[224:227], v[248:251], v[64:79]
	s_mov_b64 s[16:17], 0x30080
	s_add_u32 m0, s100, 0x13000
	v_lshl_add_u64 v[106:107], v[176:177], 0, s[16:17]
	global_load_lds_dwordx4 v[106:107], off
	v_lshl_add_u64 v[176:177], v[176:177], 0, s[18:19]
	s_waitcnt lgkmcnt(0)
	s_waitcnt vmcnt(0)
	s_barrier
	ds_read_b128 v[236:239], v170
	ds_read_b128 v[240:243], v170 offset:4096
	ds_read_b128 v[224:227], v162 offset:24576
	v_mfma_f32_32x32x16_bf16 v[48:63], v[228:231], v[244:247], v[48:63]
	v_mfma_f32_32x32x16_bf16 v[32:47], v[228:231], v[248:251], v[32:47]
	ds_read_b128 v[228:231], v162 offset:28672
	v_mfma_f32_32x32x16_bf16 v[16:31], v[232:235], v[244:247], v[16:31]
	v_mfma_f32_32x32x16_bf16 v[0:15], v[232:235], v[248:251], v[0:15]
	s_cmp_eq_u32 s15, 14
	s_cbranch_scc1 .Lga_last
	ds_read_b128 v[232:235], v162 offset:32768
	s_waitcnt lgkmcnt(2)
	v_mfma_f32_32x32x16_bf16 v[80:95], v[224:227], v[236:239], v[80:95]
	v_mfma_f32_32x32x16_bf16 v[64:79], v[224:227], v[240:243], v[64:79]
	s_mov_b32 m0, s100
	v_lshl_add_u64 v[106:107], v[174:175], 0, s[96:97]
	global_load_lds_dwordx4 v[106:107], off
	ds_read_b128 v[244:247], v171
	ds_read_b128 v[248:251], v171 offset:4096
	ds_read_b128 v[224:227], v163 offset:24576
	s_waitcnt lgkmcnt(4)
	v_mfma_f32_32x32x16_bf16 v[48:63], v[228:231], v[236:239], v[48:63]
	v_mfma_f32_32x32x16_bf16 v[32:47], v[228:231], v[240:243], v[32:47]
	s_add_u32 m0, s100, 0x1000
	v_lshl_add_u64 v[106:107], v[174:175], 0, s[50:51]
	global_load_lds_dwordx4 v[106:107], off
	ds_read_b128 v[228:231], v163 offset:28672
	s_waitcnt lgkmcnt(4)
	v_mfma_f32_32x32x16_bf16 v[16:31], v[232:235], v[236:239], v[16:31]
	v_mfma_f32_32x32x16_bf16 v[0:15], v[232:235], v[240:243], v[0:15]
	s_add_u32 m0, s100, 0x2000
	v_lshl_add_u64 v[106:107], v[174:175], 0, s[24:25]
	global_load_lds_dwordx4 v[106:107], off
	ds_read_b128 v[232:235], v163 offset:32768
	s_waitcnt lgkmcnt(2)
	v_mfma_f32_32x32x16_bf16 v[80:95], v[224:227], v[244:247], v[80:95]
	v_mfma_f32_32x32x16_bf16 v[64:79], v[224:227], v[248:251], v[64:79]
	s_add_u32 m0, s100, 0x3000
	v_lshl_add_u64 v[106:107], v[174:175], 0, s[26:27]
	global_load_lds_dwordx4 v[106:107], off
	ds_read_b128 v[236:239], v172
	ds_read_b128 v[240:243], v172 offset:4096
	ds_read_b128 v[224:227], v164 offset:24576
	s_waitcnt lgkmcnt(4)
	v_mfma_f32_32x32x16_bf16 v[48:63], v[228:231], v[244:247], v[48:63]
	v_mfma_f32_32x32x16_bf16 v[32:47], v[228:231], v[248:251], v[32:47]
	s_add_u32 m0, s100, 0x4000
	v_lshl_add_u64 v[106:107], v[174:175], 0, s[28:29]
	global_load_lds_dwordx4 v[106:107], off
	ds_read_b128 v[228:231], v164 offset:28672
	s_waitcnt lgkmcnt(4)
	v_mfma_f32_32x32x16_bf16 v[16:31], v[232:235], v[244:247], v[16:31]
	v_mfma_f32_32x32x16_bf16 v[0:15], v[232:235], v[248:251], v[0:15]
	s_add_u32 m0, s100, 0x5000
	v_lshl_add_u64 v[106:107], v[174:175], 0, s[30:31]
	global_load_lds_dwordx4 v[106:107], off
	v_lshl_add_u64 v[174:175], v[174:175], 0, s[18:19]
	ds_read_b128 v[232:235], v164 offset:32768
	s_waitcnt lgkmcnt(2)
	v_mfma_f32_32x32x16_bf16 v[80:95], v[224:227], v[236:239], v[80:95]
	v_mfma_f32_32x32x16_bf16 v[64:79], v[224:227], v[240:243], v[64:79]
	s_add_u32 m0, s100, 0xc000
	v_lshl_add_u64 v[106:107], v[176:177], 0, s[18:19]
	global_load_lds_dwordx4 v[106:107], off
	ds_read_b128 v[244:247], v173
	ds_read_b128 v[248:251], v173 offset:4096
	ds_read_b128 v[224:227], v165 offset:24576
	s_waitcnt lgkmcnt(4)
	v_mfma_f32_32x32x16_bf16 v[48:63], v[228:231], v[236:239], v[48:63]
	v_mfma_f32_32x32x16_bf16 v[32:47], v[228:231], v[240:243], v[32:47]
	s_add_u32 m0, s100, 0xd000
	v_lshl_add_u64 v[106:107], v[176:177], 0, s[42:43]
	global_load_lds_dwordx4 v[106:107], off
	ds_read_b128 v[228:231], v165 offset:28672
	s_waitcnt lgkmcnt(4)
	v_mfma_f32_32x32x16_bf16 v[16:31], v[232:235], v[236:239], v[16:31]
	v_mfma_f32_32x32x16_bf16 v[0:15], v[232:235], v[240:243], v[0:15]
	s_mov_b64 s[16:17], 0x20080
	s_add_u32 m0, s100, 0xe000
	v_lshl_add_u64 v[106:107], v[176:177], 0, s[16:17]
	global_load_lds_dwordx4 v[106:107], off
	ds_read_b128 v[232:235], v165 offset:32768
	s_waitcnt lgkmcnt(2)
	v_mfma_f32_32x32x16_bf16 v[80:95], v[224:227], v[244:247], v[80:95]
	v_mfma_f32_32x32x16_bf16 v[64:79], v[224:227], v[248:251], v[64:79]
	s_mov_b64 s[16:17], 0x30080
	s_add_u32 m0, s100, 0xf000
	v_lshl_add_u64 v[106:107], v[176:177], 0, s[16:17]
	global_load_lds_dwordx4 v[106:107], off
	v_lshl_add_u64 v[176:177], v[176:177], 0, s[18:19]
	s_waitcnt lgkmcnt(0)
	s_waitcnt vmcnt(0)
	s_barrier
	ds_read_b128 v[236:239], v166 offset:49152
	ds_read_b128 v[240:243], v166 offset:53248
	ds_read_b128 v[224:227], v162
	v_mfma_f32_32x32x16_bf16 v[48:63], v[228:231], v[244:247], v[48:63]
	v_mfma_f32_32x32x16_bf16 v[32:47], v[228:231], v[248:251], v[32:47]
	ds_read_b128 v[228:231], v162 offset:4096
	v_mfma_f32_32x32x16_bf16 v[16:31], v[232:235], v[244:247], v[16:31]
	v_mfma_f32_32x32x16_bf16 v[0:15], v[232:235], v[248:251], v[0:15]
	s_add_u32 s15, s15, 2
	s_branch .Lga_loop
; template <int EPI, int MI>
; DI void gemm_tile(const GemmDesc& g, int tm, int tn, char* smem) {
;     ...
;   for (int kt = 0; kt < nk; kt += 2) {
;     if (kt + 1 < nk) G_GLDS(kt + 1, 1);
;     G_COMPUTE(0);
;     asm volatile("s_waitcnt vmcnt(0)" ::: "memory");
;     __syncthreads();
;     if (kt + 1 < nk) {
;       if (kt + 2 < nk) G_GLDS(kt + 2, 0);
;       G_COMPUTE(1);
;       asm volatile("s_waitcnt vmcnt(0)" ::: "memory");
;       __syncthreads();
;     }
;   }
.Lga_last:
	ds_read_b128 v[232:235], v162 offset:32768
	s_waitcnt lgkmcnt(2)
	v_mfma_f32_32x32x16_bf16 v[80:95], v[224:227], v[236:239], v[80:95]
	v_mfma_f32_32x32x16_bf16 v[64:79], v[224:227], v[240:243], v[64:79]
	ds_read_b128 v[244:247], v171
	ds_read_b128 v[248:251], v171 offset:4096
	ds_read_b128 v[224:227], v163 offset:24576
	s_waitcnt lgkmcnt(4)
	v_mfma_f32_32x32x16_bf16 v[48:63], v[228:231], v[236:239], v[48:63]
	v_mfma_f32_32x32x16_bf16 v[32:47], v[228:231], v[240:243], v[32:47]
	ds_read_b128 v[228:231], v163 offset:28672
	s_waitcnt lgkmcnt(4)
	v_mfma_f32_32x32x16_bf16 v[16:31], v[232:235], v[236:239], v[16:31]
	v_mfma_f32_32x32x16_bf16 v[0:15], v[232:235], v[240:243], v[0:15]
	ds_read_b128 v[232:235], v163 offset:32768
	s_waitcnt lgkmcnt(2)
	v_mfma_f32_32x32x16_bf16 v[80:95], v[224:227], v[244:247], v[80:95]
	v_mfma_f32_32x32x16_bf16 v[64:79], v[224:227], v[248:251], v[64:79]
	ds_read_b128 v[236:239], v172
	ds_read_b128 v[240:243], v172 offset:4096
	ds_read_b128 v[224:227], v164 offset:24576
	s_waitcnt lgkmcnt(4)
	v_mfma_f32_32x32x16_bf16 v[48:63], v[228:231], v[244:247], v[48:63]
	v_mfma_f32_32x32x16_bf16 v[32:47], v[228:231], v[248:251], v[32:47]
	ds_read_b128 v[228:231], v164 offset:28672
	s_waitcnt lgkmcnt(4)
	v_mfma_f32_32x32x16_bf16 v[16:31], v[232:235], v[244:247], v[16:31]
	v_mfma_f32_32x32x16_bf16 v[0:15], v[232:235], v[248:251], v[0:15]
	ds_read_b128 v[232:235], v164 offset:32768
	s_waitcnt lgkmcnt(2)
	v_mfma_f32_32x32x16_bf16 v[80:95], v[224:227], v[236:239], v[80:95]
	v_mfma_f32_32x32x16_bf16 v[64:79], v[224:227], v[240:243], v[64:79]
	ds_read_b128 v[244:247], v173
	ds_read_b128 v[248:251], v173 offset:4096
	ds_read_b128 v[224:227], v165 offset:24576
	s_waitcnt lgkmcnt(4)
	v_mfma_f32_32x32x16_bf16 v[48:63], v[228:231], v[236:239], v[48:63]
	v_mfma_f32_32x32x16_bf16 v[32:47], v[228:231], v[240:243], v[32:47]
	ds_read_b128 v[228:231], v165 offset:28672
	s_waitcnt lgkmcnt(4)
	v_mfma_f32_32x32x16_bf16 v[16:31], v[232:235], v[236:239], v[16:31]
	v_mfma_f32_32x32x16_bf16 v[0:15], v[232:235], v[240:243], v[0:15]
	ds_read_b128 v[232:235], v165 offset:32768
	s_waitcnt lgkmcnt(2)
	v_mfma_f32_32x32x16_bf16 v[80:95], v[224:227], v[244:247], v[80:95]
	v_mfma_f32_32x32x16_bf16 v[64:79], v[224:227], v[248:251], v[64:79]
	s_waitcnt lgkmcnt(0)
	s_barrier
	v_mfma_f32_32x32x16_bf16 v[48:63], v[228:231], v[244:247], v[48:63]
	v_mfma_f32_32x32x16_bf16 v[32:47], v[228:231], v[248:251], v[32:47]
	v_mfma_f32_32x32x16_bf16 v[16:31], v[232:235], v[244:247], v[16:31]
	v_mfma_f32_32x32x16_bf16 v[0:15], v[232:235], v[248:251], v[0:15]
	s_branch .LBB0_201

; DI void gla_chain_mfma(const P& p, int cid, char* smem) {
;     ...
;       if (tid < 64) {
;         float run = 0.f;
; #pragma unroll 8
;         for (int j = 0; j < 64; ++j) { run += BC[j * 65 + tid]; BC[j * 65 + tid] = run; }
;       }
.LBB0_727:
	s_waitcnt lgkmcnt(0)
	s_barrier
	s_and_saveexec_b64 s[54:55], s[0:1]
	s_cbranch_execz .LBB0_730
	v_mov_b32_e32 v16, 0
	ds_read_b32 v224, v156 offset:0
	ds_read_b32 v225, v156 offset:260
	ds_read_b32 v226, v156 offset:520
	ds_read_b32 v227, v156 offset:780
	ds_read_b32 v228, v156 offset:1040
	ds_read_b32 v229, v156 offset:1300
	ds_read_b32 v230, v156 offset:1560
	ds_read_b32 v231, v156 offset:1820
	ds_read_b32 v232, v156 offset:2080
	ds_read_b32 v233, v156 offset:2340
	ds_read_b32 v234, v156 offset:2600
	ds_read_b32 v235, v156 offset:2860
	ds_read_b32 v236, v156 offset:3120
	ds_read_b32 v237, v156 offset:3380
	ds_read_b32 v238, v156 offset:3640
	ds_read_b32 v239, v156 offset:3900
	ds_read_b32 v240, v156 offset:4160
	ds_read_b32 v241, v156 offset:4420
	ds_read_b32 v242, v156 offset:4680
	ds_read_b32 v243, v156 offset:4940
	ds_read_b32 v244, v156 offset:5200
	ds_read_b32 v245, v156 offset:5460
	ds_read_b32 v246, v156 offset:5720
	ds_read_b32 v247, v156 offset:5980
	ds_read_b32 v248, v156 offset:6240
	ds_read_b32 v249, v156 offset:6500
	ds_read_b32 v250, v156 offset:6760
	ds_read_b32 v251, v156 offset:7020
	ds_read_b32 v252, v156 offset:7280
	ds_read_b32 v253, v156 offset:7540
	ds_read_b32 v254, v156 offset:7800
	ds_read_b32 v255, v156 offset:8060
	s_waitcnt lgkmcnt(0)
	v_add_f32_e32 v224, v16, v224
	v_add_f32_e32 v225, v224, v225
	v_add_f32_e32 v226, v225, v226
	v_add_f32_e32 v227, v226, v227
	v_add_f32_e32 v228, v227, v228
	v_add_f32_e32 v229, v228, v229
	v_add_f32_e32 v230, v229, v230
	v_add_f32_e32 v231, v230, v231
	v_add_f32_e32 v232, v231, v232
	v_add_f32_e32 v233, v232, v233
	v_add_f32_e32 v234, v233, v234
	v_add_f32_e32 v235, v234, v235
	v_add_f32_e32 v236, v235, v236
	v_add_f32_e32 v237, v236, v237
	v_add_f32_e32 v238, v237, v238
	v_add_f32_e32 v239, v238, v239
	v_add_f32_e32 v240, v239, v240
	v_add_f32_e32 v241, v240, v241
	v_add_f32_e32 v242, v241, v242
	v_add_f32_e32 v243, v242, v243
	v_add_f32_e32 v244, v243, v244
	v_add_f32_e32 v245, v244, v245
	v_add_f32_e32 v246, v245, v246
	v_add_f32_e32 v247, v246, v247
	v_add_f32_e32 v248, v247, v248
	v_add_f32_e32 v249, v248, v249
	v_add_f32_e32 v250, v249, v250
	v_add_f32_e32 v251, v250, v251
	v_add_f32_e32 v252, v251, v252
	v_add_f32_e32 v253, v252, v253
	v_add_f32_e32 v254, v253, v254
	v_add_f32_e32 v255, v254, v255
	v_mov_b32_e32 v16, v255
	ds_write_b32 v156, v224 offset:0
	ds_write_b32 v156, v225 offset:260
	ds_write_b32 v156, v226 offset:520
	ds_write_b32 v156, v227 offset:780
	ds_write_b32 v156, v228 offset:1040
	ds_write_b32 v156, v229 offset:1300
	ds_write_b32 v156, v230 offset:1560
	ds_write_b32 v156, v231 offset:1820
	ds_write_b32 v156, v232 offset:2080
	ds_write_b32 v156, v233 offset:2340
	ds_write_b32 v156, v234 offset:2600
	ds_write_b32 v156, v235 offset:2860
	ds_write_b32 v156, v236 offset:3120
	ds_write_b32 v156, v237 offset:3380
	ds_write_b32 v156, v238 offset:3640
	ds_write_b32 v156, v239 offset:3900
	ds_write_b32 v156, v240 offset:4160
	ds_write_b32 v156, v241 offset:4420
	ds_write_b32 v156, v242 offset:4680
	ds_write_b32 v156, v243 offset:4940
	ds_write_b32 v156, v244 offset:5200
	ds_write_b32 v156, v245 offset:5460
	ds_write_b32 v156, v246 offset:5720
	ds_write_b32 v156, v247 offset:5980
	ds_write_b32 v156, v248 offset:6240
	ds_write_b32 v156, v249 offset:6500
	ds_write_b32 v156, v250 offset:6760
	ds_write_b32 v156, v251 offset:7020
	ds_write_b32 v156, v252 offset:7280
	ds_write_b32 v156, v253 offset:7540
	ds_write_b32 v156, v254 offset:7800
	ds_write_b32 v156, v255 offset:8060
	ds_read_b32 v224, v156 offset:8320
	ds_read_b32 v225, v156 offset:8580
	ds_read_b32 v226, v156 offset:8840
	ds_read_b32 v227, v156 offset:9100
	ds_read_b32 v228, v156 offset:9360
	ds_read_b32 v229, v156 offset:9620
	ds_read_b32 v230, v156 offset:9880
	ds_read_b32 v231, v156 offset:10140
	ds_read_b32 v232, v156 offset:10400
	ds_read_b32 v233, v156 offset:10660
	ds_read_b32 v234, v156 offset:10920
	ds_read_b32 v235, v156 offset:11180
	ds_read_b32 v236, v156 offset:11440
	ds_read_b32 v237, v156 offset:11700
	ds_read_b32 v238, v156 offset:11960
	ds_read_b32 v239, v156 offset:12220
	ds_read_b32 v240, v156 offset:12480
	ds_read_b32 v241, v156 offset:12740
	ds_read_b32 v242, v156 offset:13000
	ds_read_b32 v243, v156 offset:13260
	ds_read_b32 v244, v156 offset:13520
	ds_read_b32 v245, v156 offset:13780
	ds_read_b32 v246, v156 offset:14040
	ds_read_b32 v247, v156 offset:14300
	ds_read_b32 v248, v156 offset:14560
	ds_read_b32 v249, v156 offset:14820
	ds_read_b32 v250, v156 offset:15080
	ds_read_b32 v251, v156 offset:15340
	ds_read_b32 v252, v156 offset:15600
	ds_read_b32 v253, v156 offset:15860
	ds_read_b32 v254, v156 offset:16120
	ds_read_b32 v255, v156 offset:16380
	s_waitcnt lgkmcnt(0)
	v_add_f32_e32 v224, v16, v224
	v_add_f32_e32 v225, v224, v225
	v_add_f32_e32 v226, v225, v226
	v_add_f32_e32 v227, v226, v227
	v_add_f32_e32 v228, v227, v228
	v_add_f32_e32 v229, v228, v229
	v_add_f32_e32 v230, v229, v230
	v_add_f32_e32 v231, v230, v231
	v_add_f32_e32 v232, v231, v232
	v_add_f32_e32 v233, v232, v233
	v_add_f32_e32 v234, v233, v234
	v_add_f32_e32 v235, v234, v235
	v_add_f32_e32 v236, v235, v236
	v_add_f32_e32 v237, v236, v237
	v_add_f32_e32 v238, v237, v238
	v_add_f32_e32 v239, v238, v239
	v_add_f32_e32 v240, v239, v240
	v_add_f32_e32 v241, v240, v241
	v_add_f32_e32 v242, v241, v242
	v_add_f32_e32 v243, v242, v243
	v_add_f32_e32 v244, v243, v244
	v_add_f32_e32 v245, v244, v245
	v_add_f32_e32 v246, v245, v246
	v_add_f32_e32 v247, v246, v247
	v_add_f32_e32 v248, v247, v248
	v_add_f32_e32 v249, v248, v249
	v_add_f32_e32 v250, v249, v250
	v_add_f32_e32 v251, v250, v251
	v_add_f32_e32 v252, v251, v252
	v_add_f32_e32 v253, v252, v253
	v_add_f32_e32 v254, v253, v254
	v_add_f32_e32 v255, v254, v255
	v_mov_b32_e32 v16, v255
	ds_write_b32 v156, v224 offset:8320
	ds_write_b32 v156, v225 offset:8580
	ds_write_b32 v156, v226 offset:8840
	ds_write_b32 v156, v227 offset:9100
	ds_write_b32 v156, v228 offset:9360
	ds_write_b32 v156, v229 offset:9620
	ds_write_b32 v156, v230 offset:9880
	ds_write_b32 v156, v231 offset:10140
	ds_write_b32 v156, v232 offset:10400
	ds_write_b32 v156, v233 offset:10660
	ds_write_b32 v156, v234 offset:10920
	ds_write_b32 v156, v235 offset:11180
	ds_write_b32 v156, v236 offset:11440
	ds_write_b32 v156, v237 offset:11700
	ds_write_b32 v156, v238 offset:11960
	ds_write_b32 v156, v239 offset:12220
	ds_write_b32 v156, v240 offset:12480
	ds_write_b32 v156, v241 offset:12740
	ds_write_b32 v156, v242 offset:13000
	ds_write_b32 v156, v243 offset:13260
	ds_write_b32 v156, v244 offset:13520
	ds_write_b32 v156, v245 offset:13780
	ds_write_b32 v156, v246 offset:14040
	ds_write_b32 v156, v247 offset:14300
	ds_write_b32 v156, v248 offset:14560
	ds_write_b32 v156, v249 offset:14820
	ds_write_b32 v156, v250 offset:15080
	ds_write_b32 v156, v251 offset:15340
	ds_write_b32 v156, v252 offset:15600
	ds_write_b32 v156, v253 offset:15860
	ds_write_b32 v156, v254 offset:16120
	ds_write_b32 v156, v255 offset:16380

; DI float silu_f(float x) { return x * __builtin_amdgcn_rcpf(1.f + __expf(-x)); }
; template <int EPI, int MI>
; DI void gemm_tile(const GemmDesc& g, int tm, int tn, char* smem) {
;     ...
;   if (EPI == EPI_SWIGLU) {
;     u16* es = (u16*)smem;
; #pragma unroll
;     for (int mi = 0; mi < MI; ++mi)
; #pragma unroll
;       for (int i = 0; i < 16; ++i) {
;         const int lrow = wm * (32 * MI) + mi * 32 + (i & 3) + 8 * (i >> 2) + 4 * hh;
;         es[lrow * 64 + wn * 32 + r] = f2bf(silu_f(acc[mi][0][i]) * acc[mi][1][i]);
;       }
.LBB0_1420:
	s_nop 1
	v_mul_f32_e32 v162, 0xbfb8aa3b, v80
	v_mul_f32_e32 v163, 0xbfb8aa3b, v81
	v_mul_f32_e32 v164, 0xbfb8aa3b, v82
	v_mul_f32_e32 v165, 0xbfb8aa3b, v83
	v_mul_f32_e32 v166, 0xbfb8aa3b, v84
	v_mul_f32_e32 v167, 0xbfb8aa3b, v85
	v_mul_f32_e32 v168, 0xbfb8aa3b, v86
	v_mul_f32_e32 v169, 0xbfb8aa3b, v87
	v_mul_f32_e32 v170, 0xbfb8aa3b, v88
	v_mul_f32_e32 v171, 0xbfb8aa3b, v89
	v_mul_f32_e32 v172, 0xbfb8aa3b, v90
	v_mul_f32_e32 v173, 0xbfb8aa3b, v91
	v_mul_f32_e32 v174, 0xbfb8aa3b, v92
	v_mul_f32_e32 v175, 0xbfb8aa3b, v93
	v_mul_f32_e32 v176, 0xbfb8aa3b, v94
	v_mul_f32_e32 v177, 0xbfb8aa3b, v95
	v_exp_f32_e32 v162, v162
	v_exp_f32_e32 v163, v163
	v_exp_f32_e32 v164, v164
	v_exp_f32_e32 v165, v165
	v_exp_f32_e32 v166, v166
	v_exp_f32_e32 v167, v167
	v_exp_f32_e32 v168, v168
	v_exp_f32_e32 v169, v169
	v_exp_f32_e32 v170, v170
	v_exp_f32_e32 v171, v171
	v_exp_f32_e32 v172, v172
	v_exp_f32_e32 v173, v173
	v_exp_f32_e32 v174, v174
	v_exp_f32_e32 v175, v175
	v_exp_f32_e32 v176, v176
	v_exp_f32_e32 v177, v177
	v_add_f32_e32 v162, 1.0, v162
	v_add_f32_e32 v163, 1.0, v163
	v_add_f32_e32 v164, 1.0, v164
	v_add_f32_e32 v165, 1.0, v165
	v_add_f32_e32 v166, 1.0, v166
	v_add_f32_e32 v167, 1.0, v167
	v_add_f32_e32 v168, 1.0, v168
	v_add_f32_e32 v169, 1.0, v169
	v_add_f32_e32 v170, 1.0, v170
	v_add_f32_e32 v171, 1.0, v171
	v_add_f32_e32 v172, 1.0, v172
	v_add_f32_e32 v173, 1.0, v173
	v_add_f32_e32 v174, 1.0, v174
	v_add_f32_e32 v175, 1.0, v175
	v_add_f32_e32 v176, 1.0, v176
	v_add_f32_e32 v177, 1.0, v177
	v_rcp_f32_e32 v162, v162
	v_rcp_f32_e32 v163, v163
	v_rcp_f32_e32 v164, v164
	v_rcp_f32_e32 v165, v165
	v_rcp_f32_e32 v166, v166
	v_rcp_f32_e32 v167, v167
	v_rcp_f32_e32 v168, v168
	v_rcp_f32_e32 v169, v169
	v_rcp_f32_e32 v170, v170
	v_rcp_f32_e32 v171, v171
	v_rcp_f32_e32 v172, v172
	v_rcp_f32_e32 v173, v173
	v_rcp_f32_e32 v174, v174
	v_rcp_f32_e32 v175, v175
	v_rcp_f32_e32 v176, v176
	v_rcp_f32_e32 v177, v177
	v_mul_f32_e32 v80, v80, v162
	v_mul_f32_e32 v81, v81, v163
	v_mul_f32_e32 v82, v82, v164
	v_mul_f32_e32 v83, v83, v165
	v_mul_f32_e32 v84, v84, v166
	v_mul_f32_e32 v85, v85, v167
	v_mul_f32_e32 v86, v86, v168
	v_mul_f32_e32 v87, v87, v169
	v_mul_f32_e32 v88, v88, v170
	v_mul_f32_e32 v89, v89, v171
	v_mul_f32_e32 v90, v90, v172
	v_mul_f32_e32 v91, v91, v173
	v_mul_f32_e32 v92, v92, v174
	v_mul_f32_e32 v93, v93, v175
	v_mul_f32_e32 v94, v94, v176
	v_mul_f32_e32 v95, v95, v177
	v_mul_f32_e32 v80, v64, v80
	v_mul_f32_e32 v81, v65, v81
	v_mul_f32_e32 v82, v66, v82
	v_mul_f32_e32 v83, v67, v83
	v_mul_f32_e32 v84, v68, v84
	v_mul_f32_e32 v85, v69, v85
	v_mul_f32_e32 v86, v70, v86
	v_mul_f32_e32 v87, v71, v87
	v_mul_f32_e32 v88, v72, v88
	v_mul_f32_e32 v89, v73, v89
	v_mul_f32_e32 v90, v74, v90
	v_mul_f32_e32 v91, v75, v91
	v_mul_f32_e32 v92, v76, v92
	v_mul_f32_e32 v93, v77, v93
	v_mul_f32_e32 v94, v78, v94
	v_mul_f32_e32 v95, v79, v95
	v_cvt_pk_bf16_f32 v80, v80, s0
	v_cvt_pk_bf16_f32 v81, v81, s0
	v_cvt_pk_bf16_f32 v82, v82, s0
	v_cvt_pk_bf16_f32 v83, v83, s0
	v_cvt_pk_bf16_f32 v84, v84, s0
	v_cvt_pk_bf16_f32 v85, v85, s0
	v_cvt_pk_bf16_f32 v86, v86, s0
	v_cvt_pk_bf16_f32 v87, v87, s0
	v_cvt_pk_bf16_f32 v88, v88, s0
	v_cvt_pk_bf16_f32 v89, v89, s0
	v_cvt_pk_bf16_f32 v90, v90, s0
	v_cvt_pk_bf16_f32 v91, v91, s0
	v_cvt_pk_bf16_f32 v92, v92, s0
	v_cvt_pk_bf16_f32 v93, v93, s0
	v_cvt_pk_bf16_f32 v94, v94, s0
	v_cvt_pk_bf16_f32 v95, v95, s0
	v_mul_f32_e32 v162, 0xbfb8aa3b, v48
	v_mul_f32_e32 v163, 0xbfb8aa3b, v49
	v_mul_f32_e32 v164, 0xbfb8aa3b, v50
	v_mul_f32_e32 v165, 0xbfb8aa3b, v51
	v_mul_f32_e32 v166, 0xbfb8aa3b, v52
	v_mul_f32_e32 v167, 0xbfb8aa3b, v53
	v_mul_f32_e32 v168, 0xbfb8aa3b, v54
	v_mul_f32_e32 v169, 0xbfb8aa3b, v55
	v_mul_f32_e32 v170, 0xbfb8aa3b, v56
	v_mul_f32_e32 v171, 0xbfb8aa3b, v57
	v_mul_f32_e32 v172, 0xbfb8aa3b, v58
	v_mul_f32_e32 v173, 0xbfb8aa3b, v59
	v_mul_f32_e32 v174, 0xbfb8aa3b, v60
	v_mul_f32_e32 v175, 0xbfb8aa3b, v61
	v_mul_f32_e32 v176, 0xbfb8aa3b, v62
	v_mul_f32_e32 v177, 0xbfb8aa3b, v63
	v_exp_f32_e32 v162, v162
	v_exp_f32_e32 v163, v163
	v_exp_f32_e32 v164, v164
	v_exp_f32_e32 v165, v165
	v_exp_f32_e32 v166, v166
	v_exp_f32_e32 v167, v167
	v_exp_f32_e32 v168, v168
	v_exp_f32_e32 v169, v169
	v_exp_f32_e32 v170, v170
	v_exp_f32_e32 v171, v171
	v_exp_f32_e32 v172, v172
	v_exp_f32_e32 v173, v173
	v_exp_f32_e32 v174, v174
	v_exp_f32_e32 v175, v175
	v_exp_f32_e32 v176, v176
	v_exp_f32_e32 v177, v177
	v_add_f32_e32 v162, 1.0, v162
	v_add_f32_e32 v163, 1.0, v163
	v_add_f32_e32 v164, 1.0, v164
	v_add_f32_e32 v165, 1.0, v165
	v_add_f32_e32 v166, 1.0, v166
	v_add_f32_e32 v167, 1.0, v167
	v_add_f32_e32 v168, 1.0, v168
	v_add_f32_e32 v169, 1.0, v169
	v_add_f32_e32 v170, 1.0, v170
	v_add_f32_e32 v171, 1.0, v171
	v_add_f32_e32 v172, 1.0, v172
	v_add_f32_e32 v173, 1.0, v173
	v_add_f32_e32 v174, 1.0, v174
	v_add_f32_e32 v175, 1.0, v175
	v_add_f32_e32 v176, 1.0, v176
	v_add_f32_e32 v177, 1.0, v177
	v_rcp_f32_e32 v162, v162
	v_rcp_f32_e32 v163, v163
	v_rcp_f32_e32 v164, v164
	v_rcp_f32_e32 v165, v165
	v_rcp_f32_e32 v166, v166
	v_rcp_f32_e32 v167, v167
	v_rcp_f32_e32 v168, v168
	v_rcp_f32_e32 v169, v169
	v_rcp_f32_e32 v170, v170
	v_rcp_f32_e32 v171, v171
	v_rcp_f32_e32 v172, v172
	v_rcp_f32_e32 v173, v173
	v_rcp_f32_e32 v174, v174
	v_rcp_f32_e32 v175, v175
	v_rcp_f32_e32 v176, v176
	v_rcp_f32_e32 v177, v177
	v_mul_f32_e32 v48, v48, v162
	v_mul_f32_e32 v49, v49, v163
	v_mul_f32_e32 v50, v50, v164
	v_mul_f32_e32 v51, v51, v165
	v_mul_f32_e32 v52, v52, v166
	v_mul_f32_e32 v53, v53, v167
	v_mul_f32_e32 v54, v54, v168
	v_mul_f32_e32 v55, v55, v169
	v_mul_f32_e32 v56, v56, v170
	v_mul_f32_e32 v57, v57, v171
	v_mul_f32_e32 v58, v58, v172
; DI float silu_f(float x) { return x * __builtin_amdgcn_rcpf(1.f + __expf(-x)); }
; template <int EPI, int MI>
; DI void gemm_tile(const GemmDesc& g, int tm, int tn, char* smem) {
;     ...
; #pragma unroll
;     for (int mi = 0; mi < MI; ++mi)
; #pragma unroll
;       for (int i = 0; i < 16; ++i) {
;         const int lrow = wm * (32 * MI) + mi * 32 + (i & 3) + 8 * (i >> 2) + 4 * hh;
;         es[lrow * 64 + wn * 32 + r] = f2bf(silu_f(acc[mi][0][i]) * acc[mi][1][i]);
;       }
;     __syncthreads();
	v_mul_f32_e32 v59, v59, v173
	v_mul_f32_e32 v60, v60, v174
	v_mul_f32_e32 v61, v61, v175
	v_mul_f32_e32 v62, v62, v176
	v_mul_f32_e32 v63, v63, v177
	v_mul_f32_e32 v48, v32, v48
	v_mul_f32_e32 v49, v33, v49
	v_mul_f32_e32 v50, v34, v50
	v_mul_f32_e32 v51, v35, v51
	v_mul_f32_e32 v52, v36, v52
	v_mul_f32_e32 v53, v37, v53
	v_mul_f32_e32 v54, v38, v54
	v_mul_f32_e32 v55, v39, v55
	v_mul_f32_e32 v56, v40, v56
	v_mul_f32_e32 v57, v41, v57
	v_mul_f32_e32 v58, v42, v58
	v_mul_f32_e32 v59, v43, v59
	v_mul_f32_e32 v60, v44, v60
	v_mul_f32_e32 v61, v45, v61
	v_mul_f32_e32 v62, v46, v62
	v_mul_f32_e32 v63, v47, v63
	v_cvt_pk_bf16_f32 v48, v48, s0
	v_cvt_pk_bf16_f32 v49, v49, s0
	v_cvt_pk_bf16_f32 v50, v50, s0
	v_cvt_pk_bf16_f32 v51, v51, s0
	v_cvt_pk_bf16_f32 v52, v52, s0
	v_cvt_pk_bf16_f32 v53, v53, s0
	v_cvt_pk_bf16_f32 v54, v54, s0
	v_cvt_pk_bf16_f32 v55, v55, s0
	v_cvt_pk_bf16_f32 v56, v56, s0
	v_cvt_pk_bf16_f32 v57, v57, s0
	v_cvt_pk_bf16_f32 v58, v58, s0
	v_cvt_pk_bf16_f32 v59, v59, s0
	v_cvt_pk_bf16_f32 v60, v60, s0
	v_cvt_pk_bf16_f32 v61, v61, s0
	v_cvt_pk_bf16_f32 v62, v62, s0
	v_cvt_pk_bf16_f32 v63, v63, s0
	v_mul_f32_e32 v162, 0xbfb8aa3b, v16
	v_mul_f32_e32 v163, 0xbfb8aa3b, v17
	v_mul_f32_e32 v164, 0xbfb8aa3b, v18
	v_mul_f32_e32 v165, 0xbfb8aa3b, v19
	v_mul_f32_e32 v166, 0xbfb8aa3b, v20
	v_mul_f32_e32 v167, 0xbfb8aa3b, v21
	v_mul_f32_e32 v168, 0xbfb8aa3b, v22
	v_mul_f32_e32 v169, 0xbfb8aa3b, v23
	v_mul_f32_e32 v170, 0xbfb8aa3b, v24
	v_mul_f32_e32 v171, 0xbfb8aa3b, v25
	v_mul_f32_e32 v172, 0xbfb8aa3b, v26
	v_mul_f32_e32 v173, 0xbfb8aa3b, v27
	v_mul_f32_e32 v174, 0xbfb8aa3b, v28
	v_mul_f32_e32 v175, 0xbfb8aa3b, v29
	v_mul_f32_e32 v176, 0xbfb8aa3b, v30
	v_mul_f32_e32 v177, 0xbfb8aa3b, v31
	v_exp_f32_e32 v162, v162
	v_exp_f32_e32 v163, v163
	v_exp_f32_e32 v164, v164
	v_exp_f32_e32 v165, v165
	v_exp_f32_e32 v166, v166
	v_exp_f32_e32 v167, v167
	v_exp_f32_e32 v168, v168
	v_exp_f32_e32 v169, v169
	v_exp_f32_e32 v170, v170
	v_exp_f32_e32 v171, v171
	v_exp_f32_e32 v172, v172
	v_exp_f32_e32 v173, v173
	v_exp_f32_e32 v174, v174
	v_exp_f32_e32 v175, v175
	v_exp_f32_e32 v176, v176
	v_exp_f32_e32 v177, v177
	v_add_f32_e32 v162, 1.0, v162
	v_add_f32_e32 v163, 1.0, v163
	v_add_f32_e32 v164, 1.0, v164
	v_add_f32_e32 v165, 1.0, v165
	v_add_f32_e32 v166, 1.0, v166
	v_add_f32_e32 v167, 1.0, v167
	v_add_f32_e32 v168, 1.0, v168
	v_add_f32_e32 v169, 1.0, v169
	v_add_f32_e32 v170, 1.0, v170
	v_add_f32_e32 v171, 1.0, v171
	v_add_f32_e32 v172, 1.0, v172
	v_add_f32_e32 v173, 1.0, v173
	v_add_f32_e32 v174, 1.0, v174
	v_add_f32_e32 v175, 1.0, v175
	v_add_f32_e32 v176, 1.0, v176
	v_add_f32_e32 v177, 1.0, v177
	v_rcp_f32_e32 v162, v162
	v_rcp_f32_e32 v163, v163
	v_rcp_f32_e32 v164, v164
	v_rcp_f32_e32 v165, v165
	v_rcp_f32_e32 v166, v166
	v_rcp_f32_e32 v167, v167
	v_rcp_f32_e32 v168, v168
	v_rcp_f32_e32 v169, v169
	v_rcp_f32_e32 v170, v170
	v_rcp_f32_e32 v171, v171
	v_rcp_f32_e32 v172, v172
	v_rcp_f32_e32 v173, v173
	v_rcp_f32_e32 v174, v174
	v_rcp_f32_e32 v175, v175
	v_rcp_f32_e32 v176, v176
	v_rcp_f32_e32 v177, v177
	v_mul_f32_e32 v16, v16, v162
	v_mul_f32_e32 v17, v17, v163
	v_mul_f32_e32 v18, v18, v164
	v_mul_f32_e32 v19, v19, v165
	v_mul_f32_e32 v20, v20, v166
	v_mul_f32_e32 v21, v21, v167
	v_mul_f32_e32 v22, v22, v168
	v_mul_f32_e32 v23, v23, v169
	v_mul_f32_e32 v24, v24, v170
	v_mul_f32_e32 v25, v25, v171
	v_mul_f32_e32 v26, v26, v172
	v_mul_f32_e32 v27, v27, v173
	v_mul_f32_e32 v28, v28, v174
	v_mul_f32_e32 v29, v29, v175
	v_mul_f32_e32 v30, v30, v176
	v_mul_f32_e32 v31, v31, v177
	v_mul_f32_e32 v16, v0, v16
	v_mul_f32_e32 v17, v1, v17
	v_mul_f32_e32 v18, v2, v18
	v_mul_f32_e32 v19, v3, v19
	v_mul_f32_e32 v20, v4, v20
	v_mul_f32_e32 v21, v5, v21
	v_mul_f32_e32 v22, v6, v22
	v_mul_f32_e32 v23, v7, v23
	v_mul_f32_e32 v24, v8, v24
	v_mul_f32_e32 v25, v9, v25
	v_mul_f32_e32 v26, v10, v26
	v_mul_f32_e32 v27, v11, v27
	v_mul_f32_e32 v28, v12, v28
	v_mul_f32_e32 v29, v13, v29
	v_mul_f32_e32 v30, v14, v30
	v_mul_f32_e32 v31, v15, v31
	v_cvt_pk_bf16_f32 v16, v16, s0
	v_cvt_pk_bf16_f32 v17, v17, s0
	v_cvt_pk_bf16_f32 v18, v18, s0
	v_cvt_pk_bf16_f32 v19, v19, s0
	v_cvt_pk_bf16_f32 v20, v20, s0
	v_cvt_pk_bf16_f32 v21, v21, s0
	v_cvt_pk_bf16_f32 v22, v22, s0
	v_cvt_pk_bf16_f32 v23, v23, s0
	v_cvt_pk_bf16_f32 v24, v24, s0
	v_cvt_pk_bf16_f32 v25, v25, s0
	v_cvt_pk_bf16_f32 v26, v26, s0
	v_cvt_pk_bf16_f32 v27, v27, s0
	v_cvt_pk_bf16_f32 v28, v28, s0
	v_cvt_pk_bf16_f32 v29, v29, s0
	v_cvt_pk_bf16_f32 v30, v30, s0
	v_cvt_pk_bf16_f32 v31, v31, s0
	v_lshlrev_b32_e32 v99, 9, v122
	v_lshlrev_b32_e32 v100, 6, v123
	v_add3_u32 v99, 0, v99, v100
	v_lshlrev_b32_e32 v100, 1, v121
	v_readlane_b32 s16, v221, 5
	v_readlane_b32 s17, v221, 6
	s_movk_i32 s0, 0x3000
	v_mul_lo_u32 v64, v120, s0
	v_add3_u32 v64, v99, v100, v64
	s_movk_i32 s15, 0x1600
	v_lshlrev_b32_e32 v4, 4, v115
	v_mov_b32_e32 v5, v96
	v_mov_b64_e32 v[6:7], s[16:17]
	v_mad_i64_i32 v[8:9], s[16:17], v98, s15, v[6:7]
	v_add_u32_e32 v10, 0, v4
	v_lshl_add_u32 v0, v97, 7, v10
	ds_write_b16 v64, v80
	ds_write_b16 v64, v81 offset:128
	ds_write_b16 v64, v82 offset:256
	ds_write_b16 v64, v83 offset:384
	ds_write_b16 v64, v84 offset:1024
	ds_write_b16 v64, v85 offset:1152
	ds_write_b16 v64, v86 offset:1280
	ds_write_b16 v64, v87 offset:1408
	ds_write_b16 v64, v88 offset:2048
	ds_write_b16 v64, v89 offset:2176
	ds_write_b16 v64, v90 offset:2304
	ds_write_b16 v64, v91 offset:2432
	ds_write_b16 v64, v92 offset:3072
	ds_write_b16 v64, v93 offset:3200
	ds_write_b16 v64, v94 offset:3328
	ds_write_b16 v64, v95 offset:3456
	ds_write_b16 v64, v48 offset:4096
	ds_write_b16 v64, v49 offset:4224
	ds_write_b16 v64, v50 offset:4352
	ds_write_b16 v64, v51 offset:4480
	ds_write_b16 v64, v52 offset:5120
	ds_write_b16 v64, v53 offset:5248
	ds_write_b16 v64, v54 offset:5376
	ds_write_b16 v64, v55 offset:5504
	ds_write_b16 v64, v56 offset:6144
	ds_write_b16 v64, v57 offset:6272
	ds_write_b16 v64, v58 offset:6400
	ds_write_b16 v64, v59 offset:6528
	ds_write_b16 v64, v60 offset:7168
	ds_write_b16 v64, v61 offset:7296
	ds_write_b16 v64, v62 offset:7424
	ds_write_b16 v64, v63 offset:7552
	ds_write_b16 v64, v16 offset:8192
	ds_write_b16 v64, v17 offset:8320
	ds_write_b16 v64, v18 offset:8448
	ds_write_b16 v64, v19 offset:8576
	ds_write_b16 v64, v20 offset:9216
	ds_write_b16 v64, v21 offset:9344
	ds_write_b16 v64, v22 offset:9472
	ds_write_b16 v64, v23 offset:9600
	ds_write_b16 v64, v24 offset:10240
	ds_write_b16 v64, v25 offset:10368
	ds_write_b16 v64, v26 offset:10496
	ds_write_b16 v64, v27 offset:10624
	ds_write_b16 v64, v28 offset:11264
	ds_write_b16 v64, v29 offset:11392
	ds_write_b16 v64, v30 offset:11520
	ds_write_b16 v64, v31 offset:11648
	s_waitcnt lgkmcnt(0)
	s_barrier
; template <int EPI, int MI>
; DI void gemm_tile(const GemmDesc& g, int tm, int tn, char* smem) {
;     ...
; #pragma unroll
;     for (int j = 0; j < 2 * MI; ++j) {
;       const int lrow = (tid >> 3) + 32 * j, ch = tid & 7;
;       const u32x4 v = *(const u32x4*)(es + lrow * 64 + ch * 8);
;       *(u32x4*)(g.o16 + (size_t)(m0 + lrow) * g.ldo + (n0 >> 1) + ch * 8) = v;
;     }
;     __syncthreads();
	s_lshl_b32 s0, s39, 6
	ds_read_b128 v[0:3], v0
	s_ashr_i32 s1, s0, 31
	s_lshl_b64 s[0:1], s[0:1], 1
	v_lshl_add_u64 v[8:9], v[8:9], 0, s[0:1]
	v_lshl_add_u64 v[8:9], v[8:9], 0, v[4:5]
	s_waitcnt lgkmcnt(0)
	global_store_dwordx4 v[8:9], v[0:3], off
	v_add_u32_e32 v8, 32, v97
	s_nop 0
	v_lshl_add_u32 v0, v8, 7, v10
	ds_read_b128 v[0:3], v0
	v_add_u32_e32 v8, s38, v8
	v_mad_i64_i32 v[8:9], s[16:17], v8, s15, v[6:7]
	v_lshl_add_u64 v[8:9], v[8:9], 0, s[0:1]
	v_lshl_add_u64 v[8:9], v[8:9], 0, v[4:5]
	s_waitcnt lgkmcnt(0)
	global_store_dwordx4 v[8:9], v[0:3], off
	v_add_u32_e32 v8, 64, v97
	s_nop 0
	v_lshl_add_u32 v0, v8, 7, v10
	ds_read_b128 v[0:3], v0
	v_add_u32_e32 v8, s38, v8
	v_mad_i64_i32 v[8:9], s[16:17], v8, s15, v[6:7]
	v_lshl_add_u64 v[8:9], v[8:9], 0, s[0:1]
	v_lshl_add_u64 v[8:9], v[8:9], 0, v[4:5]
	s_waitcnt lgkmcnt(0)
	global_store_dwordx4 v[8:9], v[0:3], off
	v_add_u32_e32 v8, 0x60, v97
	s_nop 0
	v_lshl_add_u32 v0, v8, 7, v10
	ds_read_b128 v[0:3], v0
	v_add_u32_e32 v8, s38, v8
	v_mad_i64_i32 v[8:9], s[16:17], v8, s15, v[6:7]
	v_lshl_add_u64 v[8:9], v[8:9], 0, s[0:1]
	v_lshl_add_u64 v[8:9], v[8:9], 0, v[4:5]
	s_waitcnt lgkmcnt(0)
	global_store_dwordx4 v[8:9], v[0:3], off
	v_add_u32_e32 v8, 0x80, v97
	s_nop 0
	v_lshl_add_u32 v0, v8, 7, v10
	ds_read_b128 v[0:3], v0
	v_add_u32_e32 v8, s38, v8
	v_mad_i64_i32 v[8:9], s[16:17], v8, s15, v[6:7]
	v_lshl_add_u64 v[8:9], v[8:9], 0, s[0:1]
	v_lshl_add_u64 v[8:9], v[8:9], 0, v[4:5]
	s_waitcnt lgkmcnt(0)
	global_store_dwordx4 v[8:9], v[0:3], off
	v_add_u32_e32 v8, 0xa0, v97
	s_nop 0
	v_lshl_add_u32 v0, v8, 7, v10
	v_add_u32_e32 v8, s38, v8
	ds_read_b128 v[0:3], v0
	v_mad_i64_i32 v[6:7], s[16:17], v8, s15, v[6:7]
	v_lshl_add_u64 v[6:7], v[6:7], 0, s[0:1]
	v_readlane_b32 s0, v218, 38
	s_add_i32 s5, s5, s0
	v_readlane_b32 s0, v218, 31
	s_add_i32 s4, s4, s0
	v_readlane_b32 s0, v221, 7
	v_lshl_add_u64 v[4:5], v[6:7], 0, v[4:5]
	s_cmp_ge_i32 s5, s0
	s_waitcnt lgkmcnt(0)
	global_store_dwordx4 v[4:5], v[0:3], off
	s_barrier
	s_cbranch_scc1 .LBB0_1417
